# P5 epilogue: one vmcnt drain per weight set instead of one per block
# speedup vs baseline: 1.0098x; 1.0081x over previous
; #define LAS __attribute__((address_space(3)))
; __device__ __forceinline__ float ex2(float x) { return __builtin_amdgcn_exp2f(x); }
;     __device__ __forceinline__ void operator()(const f32x4 (&acc)[2][2][4][2], const Unit& u, int wr, int wc, int fr, int fq, LAS unsigned char* hb) const {
;     ...
;         for (int n = 0; n < 2; ++n) { asm volatile("" ::: "memory");
;             const int c4 = ch + 4 * n;
;             const f32x4 w0 = *(const f32x4*)(cw + 0 * DFF + c4), w1 = *(const f32x4*)(cw + 1 * DFF + c4), w2 = *(const f32x4*)(cw + 2 * DFF + c4), bs = *(const f32x4*)(cb + c4);
; #pragma unroll
;             for (int ai = 0; ai < 2; ++ai)
; #pragma unroll
;                 for (int m = 0; m < 4; ++m) { const int q = 8 * ai + 4 * wr + m, prev = q > 0 ? q - 1 : 0; const int lr = ai * HALF + wr * 64 + m * 16 + fr, R = R0 + lr;
;                     const int Rc = R < 0 ? 0 : R; const int b = Rc / LL, p = Rc - b * LL;
;                     const LAS unsigned char* hp = hb + (prev * H * NCH + chl + 4 * n) * 4;
;                     const f32x4 h1 = *(const LAS f32x4*)(hp + hr1 * NCH * 4), h2 = *(const LAS f32x4*)(hp + hr2 * NCH * 4);
;                     const f32x4 gv = acc[ai][0][m][n], uv = acc[ai][1][m][n];
;                     float o[4];
; #pragma unroll
;                     for (int j = 0; j < 4; ++j) { const float g = gv[j];
;                         float g1 = dpp_row_shr<1>(h1[j], g), g2 = dpp_row_shr<2>(h2[j], g);
;                         g1 = p >= 1 ? g1 : 0.f; g2 = p >= 2 ? g2 : 0.f;
;                         const float v = bs[j] + w2[j] * g + w1[j] * g1 + w0[j] * g2;
;                         const float a = v + 0.044715f * v * v * v;
;                         const float ge = v * __builtin_amdgcn_rcpf(1.f + ex2(-2.f * 0.7978845608028654f * 1.4426950408889634f * a));
;                         o[j] = ge * uv[j]; }
.LBB0_888:
	s_or_b64 exec, exec, s[6:7]
	v_readlane_b32 s72, v237, 30
	v_lshl_add_u32 v170, s40, 7, v116
	v_readlane_b32 s76, v237, 34
	v_readlane_b32 s77, v237, 35
	v_readlane_b32 s78, v237, 36
	v_readlane_b32 s79, v237, 37
	v_readlane_b32 s80, v237, 38
	v_readlane_b32 s81, v237, 39
	v_readlane_b32 s82, v237, 40
	v_readlane_b32 s83, v237, 41
	v_ashrrev_i32_e32 v171, 31, v170
	v_readlane_b32 s76, v237, 0
	s_waitcnt lgkmcnt(0)
	s_barrier
	v_lshlrev_b64 v[132:133], 2, v[170:171]
	v_readlane_b32 s86, v237, 44
	v_readlane_b32 s87, v237, 45
	v_readlane_b32 s77, v237, 1
	v_lshl_add_u64 v[176:177], s[18:19], 0, v[132:133]
	v_lshl_add_u64 v[172:173], s[86:87], 0, v[132:133]
	v_lshl_add_u64 v[178:179], s[76:77], 0, v[132:133]
	v_lshl_add_u64 v[174:175], s[16:17], 0, v[132:133]
	global_load_dwordx4 v[116:119], v[172:173], off
	global_load_dwordx4 v[120:123], v[174:175], off
	global_load_dwordx4 v[128:131], v[176:177], off
	global_load_dwordx4 v[132:135], v[178:179], off
	s_mul_i32 s21, s30, 0xfe
	s_add_i32 s21, s21, -2
	v_add_u32_e32 v190, s47, v144
	v_min_i32_e32 v145, 1, v144
	v_add_u32_e32 v189, s21, v190
	v_add_u32_e32 v191, 0xfffffc00, v188
	v_lshlrev_b32_e32 v187, 9, v145
	v_max_i32_e32 v192, 0, v189
	v_add_u32_e32 v144, s51, v191
	v_mul_hi_u32 v193, v192, s64
	v_add_u32_e32 v145, v144, v187
	ds_read_b128 v[148:151], v144 offset:512
	ds_read_b128 v[144:147], v145
	v_lshrrev_b32_e32 v193, 11, v193
	v_mul_i32_i24_e32 v194, 0xffffeff0, v193
	v_add_u32_e32 v192, v194, v192
	v_cmp_lt_i32_e32 vcc, 1, v190
	v_cmp_lt_i32_e64 s[8:9], 15, v192
	v_cmp_gt_i32_e64 s[6:7], s65, v189
	s_and_b64 s[8:9], vcc, s[8:9]
	s_waitcnt lgkmcnt(0)
	v_mov_b32_dpp v148, v140 row_shr:1 row_mask:0xf bank_mask:0xf
	v_mov_b32_dpp v144, v140 row_shr:2 row_mask:0xf bank_mask:0xf
	v_mov_b32_dpp v149, v141 row_shr:1 row_mask:0xf bank_mask:0xf
	v_mov_b32_dpp v145, v141 row_shr:2 row_mask:0xf bank_mask:0xf
	v_mov_b32_dpp v150, v142 row_shr:1 row_mask:0xf bank_mask:0xf
	v_mov_b32_dpp v146, v142 row_shr:2 row_mask:0xf bank_mask:0xf
	v_mov_b32_dpp v151, v143 row_shr:1 row_mask:0xf bank_mask:0xf
	v_mov_b32_dpp v147, v143 row_shr:2 row_mask:0xf bank_mask:0xf
	s_and_b64 s[26:27], s[8:9], s[6:7]
	v_lshl_add_u32 v189, v193, 12, v192
	v_readlane_b32 s73, v237, 31
	v_readlane_b32 s74, v237, 32
	v_readlane_b32 s75, v237, 33
	v_readlane_b32 s84, v237, 42
	v_readlane_b32 s85, v237, 43
	v_readlane_b32 s78, v237, 2
	v_readlane_b32 s79, v237, 3
	v_readlane_b32 s80, v237, 4
	v_readlane_b32 s81, v237, 5
	v_readlane_b32 s82, v237, 6
	v_readlane_b32 s83, v237, 7
	s_waitcnt vmcnt(0)
	s_and_saveexec_b64 s[6:7], s[26:27]
	s_cbranch_execz .LBB0_890
	v_pk_fma_f32 v[140:141], v[140:141], v[128:129], v[132:133]
	v_pk_fma_f32 v[142:143], v[142:143], v[130:131], v[134:135]
	v_pk_fma_f32 v[140:141], v[120:121], v[148:149], v[140:141]
	v_pk_fma_f32 v[142:143], v[122:123], v[150:151], v[142:143]
	v_pk_fma_f32 v[140:141], v[116:117], v[144:145], v[140:141]
	v_pk_fma_f32 v[142:143], v[118:119], v[146:147], v[142:143]
	v_mul_f32_e32 v144, 0x3d372713, v141
	v_mul_f32_e32 v144, v141, v144
	v_mul_f32_e32 v145, 0x3d372713, v140
	v_fma_f32 v144, v141, v144, v141
	v_mul_f32_e32 v145, v140, v145
	v_mul_f32_e32 v144, 0xc0135761, v144
	v_fma_f32 v145, v140, v145, v140
	v_exp_f32_e32 v144, v144
	v_mul_f32_e32 v145, 0xc0135761, v145
	v_mul_f32_e32 v146, 0x3d372713, v143
	v_exp_f32_e32 v148, v145
	v_mul_f32_e32 v146, v143, v146
	v_mul_f32_e32 v147, 0x3d372713, v142
	v_fma_f32 v146, v143, v146, v143
	v_mul_f32_e32 v147, v142, v147
	v_mul_f32_e32 v146, 0xc0135761, v146
	v_fma_f32 v147, v142, v147, v142
	v_add_f32_e32 v144, 1.0, v144
	v_exp_f32_e32 v146, v146
	v_mul_f32_e32 v147, 0xc0135761, v147
	v_rcp_f32_e32 v145, v144
	v_add_f32_e32 v144, 1.0, v148
	v_exp_f32_e32 v148, v147
	v_add_f32_e32 v146, 1.0, v146
	v_rcp_f32_e32 v144, v144
	v_rcp_f32_e32 v147, v146
	v_add_f32_e32 v146, 1.0, v148
	v_rcp_f32_e32 v146, v146
	v_pk_mul_f32 v[140:141], v[140:141], v[144:145]
	v_pk_mul_f32 v[136:137], v[136:137], v[140:141]
	v_pk_mul_f32 v[140:141], v[142:143], v[146:147]
	v_pk_mul_f32 v[138:139], v[138:139], v[140:141]
	v_cvt_pk_bf16_f32 v196, v136, v137
	v_cvt_pk_bf16_f32 v197, v138, v139
.LBB0_890:
	s_or_b64 exec, exec, s[6:7]
	v_add_u32_e32 v144, 16, v190
	v_add_u32_e32 v145, s21, v144
	v_max_i32_e32 v146, 0, v145
	v_add_u32_e32 v136, s52, v191
	v_mul_hi_u32 v147, v146, s64
	v_add_u32_e32 v137, v136, v187
	ds_read_b128 v[140:143], v136 offset:512
	ds_read_b128 v[136:139], v137
	v_lshrrev_b32_e32 v147, 11, v147
	v_mul_i32_i24_e32 v148, 0xffffeff0, v147
	v_add_u32_e32 v146, v148, v146
	v_cmp_lt_i32_e32 vcc, 1, v144
	v_cmp_lt_i32_e64 s[8:9], 15, v146
	v_cmp_gt_i32_e64 s[6:7], s65, v145
	s_and_b64 s[8:9], vcc, s[8:9]
	s_waitcnt lgkmcnt(0)
	v_mov_b32_dpp v140, v124 row_shr:1 row_mask:0xf bank_mask:0xf
	v_mov_b32_dpp v136, v124 row_shr:2 row_mask:0xf bank_mask:0xf
	v_mov_b32_dpp v141, v125 row_shr:1 row_mask:0xf bank_mask:0xf
	v_mov_b32_dpp v137, v125 row_shr:2 row_mask:0xf bank_mask:0xf
	v_mov_b32_dpp v142, v126 row_shr:1 row_mask:0xf bank_mask:0xf
	v_mov_b32_dpp v138, v126 row_shr:2 row_mask:0xf bank_mask:0xf
	v_mov_b32_dpp v143, v127 row_shr:1 row_mask:0xf bank_mask:0xf
	v_mov_b32_dpp v139, v127 row_shr:2 row_mask:0xf bank_mask:0xf
	s_and_b64 s[28:29], s[8:9], s[6:7]
	v_lshl_add_u32 v144, v147, 12, v146
	s_and_saveexec_b64 s[6:7], s[28:29]
	s_cbranch_execz .LBB0_892
	v_pk_fma_f32 v[124:125], v[124:125], v[128:129], v[132:133]
	v_pk_fma_f32 v[126:127], v[126:127], v[130:131], v[134:135]
	v_pk_fma_f32 v[124:125], v[120:121], v[140:141], v[124:125]
	v_pk_fma_f32 v[126:127], v[122:123], v[142:143], v[126:127]
	v_pk_fma_f32 v[124:125], v[116:117], v[136:137], v[124:125]
	v_pk_fma_f32 v[126:127], v[118:119], v[138:139], v[126:127]
	v_mul_f32_e32 v136, 0x3d372713, v125
	v_mul_f32_e32 v136, v125, v136
	v_mul_f32_e32 v137, 0x3d372713, v124
	v_fma_f32 v136, v125, v136, v125
	v_mul_f32_e32 v137, v124, v137
	v_mul_f32_e32 v136, 0xc0135761, v136
	v_fma_f32 v137, v124, v137, v124
	v_exp_f32_e32 v136, v136
	v_mul_f32_e32 v137, 0xc0135761, v137
	v_mul_f32_e32 v138, 0x3d372713, v127
	v_exp_f32_e32 v140, v137
	v_mul_f32_e32 v138, v127, v138
	v_mul_f32_e32 v139, 0x3d372713, v126
	v_fma_f32 v138, v127, v138, v127
	v_mul_f32_e32 v139, v126, v139
	v_mul_f32_e32 v138, 0xc0135761, v138
	v_fma_f32 v139, v126, v139, v126
	v_add_f32_e32 v136, 1.0, v136
	v_exp_f32_e32 v138, v138
	v_mul_f32_e32 v139, 0xc0135761, v139
	v_rcp_f32_e32 v137, v136
	v_add_f32_e32 v136, 1.0, v140
	v_exp_f32_e32 v140, v139
	v_add_f32_e32 v138, 1.0, v138
	v_rcp_f32_e32 v136, v136
	v_rcp_f32_e32 v139, v138
	v_add_f32_e32 v138, 1.0, v140
	v_rcp_f32_e32 v138, v138
	v_pk_mul_f32 v[124:125], v[124:125], v[136:137]
	v_pk_mul_f32 v[112:113], v[112:113], v[124:125]
	v_pk_mul_f32 v[124:125], v[126:127], v[138:139]
	v_pk_mul_f32 v[114:115], v[114:115], v[124:125]
	v_cvt_pk_bf16_f32 v200, v112, v113
	v_cvt_pk_bf16_f32 v201, v114, v115
; #define LAS __attribute__((address_space(3)))
; __device__ __forceinline__ float ex2(float x) { return __builtin_amdgcn_exp2f(x); }
;     __device__ __forceinline__ void operator()(const f32x4 (&acc)[2][2][4][2], const Unit& u, int wr, int wc, int fr, int fq, LAS unsigned char* hb) const {
;     ...
;                 for (int m = 0; m < 4; ++m) { const int q = 8 * ai + 4 * wr + m, prev = q > 0 ? q - 1 : 0; const int lr = ai * HALF + wr * 64 + m * 16 + fr, R = R0 + lr;
;                     const int Rc = R < 0 ? 0 : R; const int b = Rc / LL, p = Rc - b * LL;
;                     const LAS unsigned char* hp = hb + (prev * H * NCH + chl + 4 * n) * 4;
;                     const f32x4 h1 = *(const LAS f32x4*)(hp + hr1 * NCH * 4), h2 = *(const LAS f32x4*)(hp + hr2 * NCH * 4);
;                     const f32x4 gv = acc[ai][0][m][n], uv = acc[ai][1][m][n];
;                     float o[4];
; #pragma unroll
;                     for (int j = 0; j < 4; ++j) { const float g = gv[j];
;                         float g1 = dpp_row_shr<1>(h1[j], g), g2 = dpp_row_shr<2>(h2[j], g);
;                         g1 = p >= 1 ? g1 : 0.f; g2 = p >= 2 ? g2 : 0.f;
;                         const float v = bs[j] + w2[j] * g + w1[j] * g1 + w0[j] * g2;
;                         const float a = v + 0.044715f * v * v * v;
;                         const float ge = v * __builtin_amdgcn_rcpf(1.f + ex2(-2.f * 0.7978845608028654f * 1.4426950408889634f * a));
;                         o[j] = ge * uv[j]; }
.LBB0_892:
	s_or_b64 exec, exec, s[6:7]
	v_add_u32_e32 v136, 32, v190
	v_add_u32_e32 v137, s21, v136
	v_max_i32_e32 v138, 0, v137
	v_add_u32_e32 v112, s53, v191
	v_mul_hi_u32 v139, v138, s64
	v_add_u32_e32 v113, v112, v187
	ds_read_b128 v[124:127], v112 offset:512
	ds_read_b128 v[112:115], v113
	v_lshrrev_b32_e32 v139, 11, v139
	v_mul_i32_i24_e32 v140, 0xffffeff0, v139
	v_add_u32_e32 v138, v140, v138
	v_cmp_lt_i32_e32 vcc, 1, v136
	v_cmp_lt_i32_e64 s[8:9], 15, v138
	v_cmp_gt_i32_e64 s[6:7], s65, v137
	s_and_b64 s[8:9], vcc, s[8:9]
	s_waitcnt lgkmcnt(0)
	v_mov_b32_dpp v124, v108 row_shr:1 row_mask:0xf bank_mask:0xf
	v_mov_b32_dpp v112, v108 row_shr:2 row_mask:0xf bank_mask:0xf
	v_mov_b32_dpp v125, v109 row_shr:1 row_mask:0xf bank_mask:0xf
	v_mov_b32_dpp v113, v109 row_shr:2 row_mask:0xf bank_mask:0xf
	v_mov_b32_dpp v126, v110 row_shr:1 row_mask:0xf bank_mask:0xf
	v_mov_b32_dpp v114, v110 row_shr:2 row_mask:0xf bank_mask:0xf
	v_mov_b32_dpp v127, v111 row_shr:1 row_mask:0xf bank_mask:0xf
	v_mov_b32_dpp v115, v111 row_shr:2 row_mask:0xf bank_mask:0xf
	s_and_b64 s[30:31], s[8:9], s[6:7]
	v_lshl_add_u32 v136, v139, 12, v138
	s_and_saveexec_b64 s[6:7], s[30:31]
	s_cbranch_execz .LBB0_894
	v_pk_fma_f32 v[108:109], v[108:109], v[128:129], v[132:133]
	v_pk_fma_f32 v[110:111], v[110:111], v[130:131], v[134:135]
	v_pk_fma_f32 v[108:109], v[120:121], v[124:125], v[108:109]
	v_pk_fma_f32 v[110:111], v[122:123], v[126:127], v[110:111]
	v_pk_fma_f32 v[108:109], v[116:117], v[112:113], v[108:109]
	v_pk_fma_f32 v[110:111], v[118:119], v[114:115], v[110:111]
	v_mul_f32_e32 v112, 0x3d372713, v109
	v_mul_f32_e32 v112, v109, v112
	v_mul_f32_e32 v113, 0x3d372713, v108
	v_fma_f32 v112, v109, v112, v109
	v_mul_f32_e32 v113, v108, v113
	v_mul_f32_e32 v112, 0xc0135761, v112
	v_fma_f32 v113, v108, v113, v108
	v_exp_f32_e32 v112, v112
	v_mul_f32_e32 v113, 0xc0135761, v113
	v_mul_f32_e32 v114, 0x3d372713, v111
	v_exp_f32_e32 v124, v113
	v_mul_f32_e32 v114, v111, v114
	v_mul_f32_e32 v115, 0x3d372713, v110
	v_fma_f32 v114, v111, v114, v111
	v_mul_f32_e32 v115, v110, v115
	v_mul_f32_e32 v114, 0xc0135761, v114
	v_fma_f32 v115, v110, v115, v110
	v_add_f32_e32 v112, 1.0, v112
	v_exp_f32_e32 v114, v114
	v_mul_f32_e32 v115, 0xc0135761, v115
	v_rcp_f32_e32 v113, v112
	v_add_f32_e32 v112, 1.0, v124
	v_exp_f32_e32 v124, v115
	v_add_f32_e32 v114, 1.0, v114
	v_rcp_f32_e32 v112, v112
	v_rcp_f32_e32 v115, v114
	v_add_f32_e32 v114, 1.0, v124
	v_rcp_f32_e32 v114, v114
	v_pk_mul_f32 v[108:109], v[108:109], v[112:113]
	v_pk_mul_f32 v[104:105], v[104:105], v[108:109]
	v_pk_mul_f32 v[108:109], v[110:111], v[114:115]
	v_pk_mul_f32 v[106:107], v[106:107], v[108:109]
	v_cvt_pk_bf16_f32 v204, v104, v105
	v_cvt_pk_bf16_f32 v205, v106, v107
.LBB0_894:
	s_or_b64 exec, exec, s[6:7]
	v_add_u32_e32 v112, 48, v190
	v_add_u32_e32 v113, s21, v112
	v_max_i32_e32 v114, 0, v113
	v_add_u32_e32 v104, s54, v191
	v_mul_hi_u32 v115, v114, s64
	v_add_u32_e32 v105, v104, v187
	ds_read_b128 v[108:111], v104 offset:512
	ds_read_b128 v[104:107], v105
	v_lshrrev_b32_e32 v115, 11, v115
	v_mul_i32_i24_e32 v124, 0xffffeff0, v115
	v_add_u32_e32 v114, v124, v114
	v_cmp_lt_i32_e32 vcc, 1, v112
	v_cmp_lt_i32_e64 s[8:9], 15, v114
	v_cmp_gt_i32_e64 s[6:7], s65, v113
	s_and_b64 s[8:9], vcc, s[8:9]
	s_waitcnt lgkmcnt(0)
	v_mov_b32_dpp v108, v100 row_shr:1 row_mask:0xf bank_mask:0xf
	v_mov_b32_dpp v104, v100 row_shr:2 row_mask:0xf bank_mask:0xf
	v_mov_b32_dpp v109, v101 row_shr:1 row_mask:0xf bank_mask:0xf
	v_mov_b32_dpp v105, v101 row_shr:2 row_mask:0xf bank_mask:0xf
	v_mov_b32_dpp v110, v102 row_shr:1 row_mask:0xf bank_mask:0xf
	v_mov_b32_dpp v106, v102 row_shr:2 row_mask:0xf bank_mask:0xf
	v_mov_b32_dpp v111, v103 row_shr:1 row_mask:0xf bank_mask:0xf
	v_mov_b32_dpp v107, v103 row_shr:2 row_mask:0xf bank_mask:0xf
	s_and_b64 s[34:35], s[8:9], s[6:7]
	v_lshl_add_u32 v112, v115, 12, v114
	s_and_saveexec_b64 s[6:7], s[34:35]
	s_cbranch_execz .LBB0_896
	v_pk_fma_f32 v[100:101], v[100:101], v[128:129], v[132:133]
	v_pk_fma_f32 v[102:103], v[102:103], v[130:131], v[134:135]
	v_pk_fma_f32 v[100:101], v[120:121], v[108:109], v[100:101]
	v_pk_fma_f32 v[102:103], v[122:123], v[110:111], v[102:103]
	v_pk_fma_f32 v[100:101], v[116:117], v[104:105], v[100:101]
	v_pk_fma_f32 v[102:103], v[118:119], v[106:107], v[102:103]
	v_mul_f32_e32 v104, 0x3d372713, v101
	v_mul_f32_e32 v104, v101, v104
	v_mul_f32_e32 v105, 0x3d372713, v100
	v_fma_f32 v104, v101, v104, v101
	v_mul_f32_e32 v105, v100, v105
	v_mul_f32_e32 v104, 0xc0135761, v104
	v_fma_f32 v105, v100, v105, v100
	v_exp_f32_e32 v104, v104
	v_mul_f32_e32 v105, 0xc0135761, v105
	v_mul_f32_e32 v106, 0x3d372713, v103
	v_exp_f32_e32 v108, v105
	v_mul_f32_e32 v106, v103, v106
	v_mul_f32_e32 v107, 0x3d372713, v102
	v_fma_f32 v106, v103, v106, v103
	v_mul_f32_e32 v107, v102, v107
	v_mul_f32_e32 v106, 0xc0135761, v106
	v_fma_f32 v107, v102, v107, v102
	v_add_f32_e32 v104, 1.0, v104
	v_exp_f32_e32 v106, v106
	v_mul_f32_e32 v107, 0xc0135761, v107
	v_rcp_f32_e32 v105, v104
	v_add_f32_e32 v104, 1.0, v108
	v_exp_f32_e32 v108, v107
	v_add_f32_e32 v106, 1.0, v106
	v_rcp_f32_e32 v104, v104
	v_rcp_f32_e32 v107, v106
	v_add_f32_e32 v106, 1.0, v108
	v_rcp_f32_e32 v106, v106
	v_pk_mul_f32 v[100:101], v[100:101], v[104:105]
	v_pk_mul_f32 v[96:97], v[96:97], v[100:101]
	v_pk_mul_f32 v[100:101], v[102:103], v[106:107]
	v_pk_mul_f32 v[98:99], v[98:99], v[100:101]
	v_cvt_pk_bf16_f32 v208, v96, v97
	v_cvt_pk_bf16_f32 v209, v98, v99
; #define LAS __attribute__((address_space(3)))
; __device__ __forceinline__ float ex2(float x) { return __builtin_amdgcn_exp2f(x); }
;     __device__ __forceinline__ void operator()(const f32x4 (&acc)[2][2][4][2], const Unit& u, int wr, int wc, int fr, int fq, LAS unsigned char* hb) const {
;     ...
;                 for (int m = 0; m < 4; ++m) { const int q = 8 * ai + 4 * wr + m, prev = q > 0 ? q - 1 : 0; const int lr = ai * HALF + wr * 64 + m * 16 + fr, R = R0 + lr;
;                     const int Rc = R < 0 ? 0 : R; const int b = Rc / LL, p = Rc - b * LL;
;                     const LAS unsigned char* hp = hb + (prev * H * NCH + chl + 4 * n) * 4;
;                     const f32x4 h1 = *(const LAS f32x4*)(hp + hr1 * NCH * 4), h2 = *(const LAS f32x4*)(hp + hr2 * NCH * 4);
;                     const f32x4 gv = acc[ai][0][m][n], uv = acc[ai][1][m][n];
;                     float o[4];
; #pragma unroll
;                     for (int j = 0; j < 4; ++j) { const float g = gv[j];
;                         float g1 = dpp_row_shr<1>(h1[j], g), g2 = dpp_row_shr<2>(h2[j], g);
;                         g1 = p >= 1 ? g1 : 0.f; g2 = p >= 2 ? g2 : 0.f;
;                         const float v = bs[j] + w2[j] * g + w1[j] * g1 + w0[j] * g2;
;                         const float a = v + 0.044715f * v * v * v;
;                         const float ge = v * __builtin_amdgcn_rcpf(1.f + ex2(-2.f * 0.7978845608028654f * 1.4426950408889634f * a));
;                         o[j] = ge * uv[j]; }
.LBB0_896:
	s_or_b64 exec, exec, s[6:7]
	v_add_u32_e32 v104, 0x80, v190
	v_add_u32_e32 v107, s21, v104
	v_max_i32_e32 v108, 0, v107
	v_mul_hi_u32 v109, v108, s64
	v_add_u32_e32 v105, s55, v188
	v_add_u32_e32 v106, v105, v187
	ds_read_b128 v[100:103], v105 offset:7680
	ds_read_b128 v[96:99], v106 offset:7168
	v_lshrrev_b32_e32 v109, 11, v109
	v_mul_i32_i24_e32 v110, 0xffffeff0, v109
	v_add_u32_e32 v108, v110, v108
	v_cmp_lt_i32_e32 vcc, 1, v104
	v_cmp_lt_i32_e64 s[8:9], 15, v108
	v_cmp_gt_i32_e64 s[6:7], s65, v107
	s_and_b64 s[8:9], vcc, s[8:9]
	s_waitcnt lgkmcnt(0)
	v_mov_b32_dpp v100, v92 row_shr:1 row_mask:0xf bank_mask:0xf
	v_mov_b32_dpp v96, v92 row_shr:2 row_mask:0xf bank_mask:0xf
	v_mov_b32_dpp v101, v93 row_shr:1 row_mask:0xf bank_mask:0xf
	v_mov_b32_dpp v97, v93 row_shr:2 row_mask:0xf bank_mask:0xf
	v_mov_b32_dpp v102, v94 row_shr:1 row_mask:0xf bank_mask:0xf
	v_mov_b32_dpp v98, v94 row_shr:2 row_mask:0xf bank_mask:0xf
	v_mov_b32_dpp v103, v95 row_shr:1 row_mask:0xf bank_mask:0xf
	v_mov_b32_dpp v99, v95 row_shr:2 row_mask:0xf bank_mask:0xf
	s_and_b64 s[36:37], s[8:9], s[6:7]
	v_lshl_add_u32 v104, v109, 12, v108
	s_and_saveexec_b64 s[6:7], s[36:37]
	s_cbranch_execz .LBB0_898
	v_pk_fma_f32 v[92:93], v[92:93], v[128:129], v[132:133]
	v_pk_fma_f32 v[94:95], v[94:95], v[130:131], v[134:135]
	v_pk_fma_f32 v[92:93], v[120:121], v[100:101], v[92:93]
	v_pk_fma_f32 v[94:95], v[122:123], v[102:103], v[94:95]
	v_pk_fma_f32 v[92:93], v[116:117], v[96:97], v[92:93]
	v_pk_fma_f32 v[94:95], v[118:119], v[98:99], v[94:95]
	v_mul_f32_e32 v96, 0x3d372713, v93
	v_mul_f32_e32 v96, v93, v96
	v_mul_f32_e32 v97, 0x3d372713, v92
	v_fma_f32 v96, v93, v96, v93
	v_mul_f32_e32 v97, v92, v97
	v_mul_f32_e32 v96, 0xc0135761, v96
	v_fma_f32 v97, v92, v97, v92
	v_exp_f32_e32 v96, v96
	v_mul_f32_e32 v97, 0xc0135761, v97
	v_mul_f32_e32 v98, 0x3d372713, v95
	v_exp_f32_e32 v100, v97
	v_mul_f32_e32 v98, v95, v98
	v_mul_f32_e32 v99, 0x3d372713, v94
	v_fma_f32 v98, v95, v98, v95
	v_mul_f32_e32 v99, v94, v99
	v_mul_f32_e32 v98, 0xc0135761, v98
	v_fma_f32 v99, v94, v99, v94
	v_add_f32_e32 v96, 1.0, v96
	v_exp_f32_e32 v98, v98
	v_mul_f32_e32 v99, 0xc0135761, v99
	v_rcp_f32_e32 v97, v96
	v_add_f32_e32 v96, 1.0, v100
	v_exp_f32_e32 v100, v99
	v_add_f32_e32 v98, 1.0, v98
	v_rcp_f32_e32 v96, v96
	v_rcp_f32_e32 v99, v98
	v_add_f32_e32 v98, 1.0, v100
	v_rcp_f32_e32 v98, v98
	v_pk_mul_f32 v[92:93], v[92:93], v[96:97]
	v_pk_mul_f32 v[88:89], v[88:89], v[92:93]
	v_pk_mul_f32 v[92:93], v[94:95], v[98:99]
	v_pk_mul_f32 v[90:91], v[90:91], v[92:93]
	v_cvt_pk_bf16_f32 v212, v88, v89
	v_cvt_pk_bf16_f32 v213, v90, v91
.LBB0_898:
	s_or_b64 exec, exec, s[6:7]
	v_add_u32_e32 v96, 0x90, v190
	v_add_u32_e32 v99, s21, v96
	v_max_i32_e32 v100, 0, v99
	v_mul_hi_u32 v101, v100, s64
	v_add_u32_e32 v97, s56, v188
	v_add_u32_e32 v98, v97, v187
	ds_read_b128 v[92:95], v97 offset:8704
	ds_read_b128 v[88:91], v98 offset:8192
	v_lshrrev_b32_e32 v101, 11, v101
	v_mul_i32_i24_e32 v102, 0xffffeff0, v101
	v_add_u32_e32 v100, v102, v100
	v_cmp_lt_i32_e32 vcc, 1, v96
	v_cmp_lt_i32_e64 s[8:9], 15, v100
	v_cmp_gt_i32_e64 s[6:7], s65, v99
	s_and_b64 s[8:9], vcc, s[8:9]
	s_waitcnt lgkmcnt(0)
	v_mov_b32_dpp v92, v84 row_shr:1 row_mask:0xf bank_mask:0xf
	v_mov_b32_dpp v88, v84 row_shr:2 row_mask:0xf bank_mask:0xf
	v_mov_b32_dpp v93, v85 row_shr:1 row_mask:0xf bank_mask:0xf
	v_mov_b32_dpp v89, v85 row_shr:2 row_mask:0xf bank_mask:0xf
	v_mov_b32_dpp v94, v86 row_shr:1 row_mask:0xf bank_mask:0xf
	v_mov_b32_dpp v90, v86 row_shr:2 row_mask:0xf bank_mask:0xf
	v_mov_b32_dpp v95, v87 row_shr:1 row_mask:0xf bank_mask:0xf
	v_mov_b32_dpp v91, v87 row_shr:2 row_mask:0xf bank_mask:0xf
	s_and_b64 s[38:39], s[8:9], s[6:7]
	v_lshl_add_u32 v96, v101, 12, v100
	s_and_saveexec_b64 s[6:7], s[38:39]
	s_cbranch_execz .LBB0_900
	v_pk_fma_f32 v[84:85], v[84:85], v[128:129], v[132:133]
	v_pk_fma_f32 v[86:87], v[86:87], v[130:131], v[134:135]
	v_pk_fma_f32 v[84:85], v[120:121], v[92:93], v[84:85]
	v_pk_fma_f32 v[86:87], v[122:123], v[94:95], v[86:87]
	v_pk_fma_f32 v[84:85], v[116:117], v[88:89], v[84:85]
	v_pk_fma_f32 v[86:87], v[118:119], v[90:91], v[86:87]
	v_mul_f32_e32 v88, 0x3d372713, v85
	v_mul_f32_e32 v88, v85, v88
	v_mul_f32_e32 v89, 0x3d372713, v84
	v_fma_f32 v88, v85, v88, v85
	v_mul_f32_e32 v89, v84, v89
	v_mul_f32_e32 v88, 0xc0135761, v88
	v_fma_f32 v89, v84, v89, v84
	v_exp_f32_e32 v88, v88
	v_mul_f32_e32 v89, 0xc0135761, v89
	v_mul_f32_e32 v90, 0x3d372713, v87
	v_exp_f32_e32 v92, v89
	v_mul_f32_e32 v90, v87, v90
	v_mul_f32_e32 v91, 0x3d372713, v86
	v_fma_f32 v90, v87, v90, v87
	v_mul_f32_e32 v91, v86, v91
	v_mul_f32_e32 v90, 0xc0135761, v90
	v_fma_f32 v91, v86, v91, v86
	v_add_f32_e32 v88, 1.0, v88
	v_exp_f32_e32 v90, v90
	v_mul_f32_e32 v91, 0xc0135761, v91
	v_rcp_f32_e32 v89, v88
	v_add_f32_e32 v88, 1.0, v92
	v_exp_f32_e32 v92, v91
	v_add_f32_e32 v90, 1.0, v90
	v_rcp_f32_e32 v88, v88
	v_rcp_f32_e32 v91, v90
	v_add_f32_e32 v90, 1.0, v92
	v_rcp_f32_e32 v90, v90
	v_pk_mul_f32 v[84:85], v[84:85], v[88:89]
	v_pk_mul_f32 v[80:81], v[80:81], v[84:85]
	v_pk_mul_f32 v[84:85], v[86:87], v[90:91]
	v_pk_mul_f32 v[82:83], v[82:83], v[84:85]
	v_cvt_pk_bf16_f32 v216, v80, v81
	v_cvt_pk_bf16_f32 v217, v82, v83
; #define LAS __attribute__((address_space(3)))
; __device__ __forceinline__ float ex2(float x) { return __builtin_amdgcn_exp2f(x); }
;     __device__ __forceinline__ void operator()(const f32x4 (&acc)[2][2][4][2], const Unit& u, int wr, int wc, int fr, int fq, LAS unsigned char* hb) const {
;     ...
;                 for (int m = 0; m < 4; ++m) { const int q = 8 * ai + 4 * wr + m, prev = q > 0 ? q - 1 : 0; const int lr = ai * HALF + wr * 64 + m * 16 + fr, R = R0 + lr;
;                     const int Rc = R < 0 ? 0 : R; const int b = Rc / LL, p = Rc - b * LL;
;                     const LAS unsigned char* hp = hb + (prev * H * NCH + chl + 4 * n) * 4;
;                     const f32x4 h1 = *(const LAS f32x4*)(hp + hr1 * NCH * 4), h2 = *(const LAS f32x4*)(hp + hr2 * NCH * 4);
;                     const f32x4 gv = acc[ai][0][m][n], uv = acc[ai][1][m][n];
;                     float o[4];
; #pragma unroll
;                     for (int j = 0; j < 4; ++j) { const float g = gv[j];
;                         float g1 = dpp_row_shr<1>(h1[j], g), g2 = dpp_row_shr<2>(h2[j], g);
;                         g1 = p >= 1 ? g1 : 0.f; g2 = p >= 2 ? g2 : 0.f;
;                         const float v = bs[j] + w2[j] * g + w1[j] * g1 + w0[j] * g2;
;                         const float a = v + 0.044715f * v * v * v;
;                         const float ge = v * __builtin_amdgcn_rcpf(1.f + ex2(-2.f * 0.7978845608028654f * 1.4426950408889634f * a));
;                         o[j] = ge * uv[j]; }
.LBB0_900:
	s_or_b64 exec, exec, s[6:7]
	v_add_u32_e32 v88, 0xa0, v190
	v_add_u32_e32 v89, s21, v88
	v_max_i32_e32 v90, 0, v89
	v_mul_hi_u32 v91, v90, s64
	v_add_u32_e32 v92, s57, v188
	v_add_u32_e32 v93, v92, v187
	ds_read_b128 v[84:87], v92 offset:9728
	ds_read_b128 v[80:83], v93 offset:9216
	v_lshrrev_b32_e32 v91, 11, v91
	v_mul_i32_i24_e32 v94, 0xffffeff0, v91
	v_add_u32_e32 v90, v94, v90
	v_cmp_lt_i32_e32 vcc, 1, v88
	v_cmp_lt_i32_e64 s[8:9], 15, v90
	v_cmp_gt_i32_e64 s[6:7], s65, v89
	s_and_b64 s[8:9], vcc, s[8:9]
	s_waitcnt lgkmcnt(0)
	v_mov_b32_dpp v84, v76 row_shr:1 row_mask:0xf bank_mask:0xf
	v_mov_b32_dpp v80, v76 row_shr:2 row_mask:0xf bank_mask:0xf
	v_mov_b32_dpp v85, v77 row_shr:1 row_mask:0xf bank_mask:0xf
	v_mov_b32_dpp v81, v77 row_shr:2 row_mask:0xf bank_mask:0xf
	v_mov_b32_dpp v86, v78 row_shr:1 row_mask:0xf bank_mask:0xf
	v_mov_b32_dpp v82, v78 row_shr:2 row_mask:0xf bank_mask:0xf
	v_mov_b32_dpp v87, v79 row_shr:1 row_mask:0xf bank_mask:0xf
	v_mov_b32_dpp v83, v79 row_shr:2 row_mask:0xf bank_mask:0xf
	s_and_b64 s[40:41], s[8:9], s[6:7]
	v_lshl_add_u32 v90, v91, 12, v90
	s_and_saveexec_b64 s[6:7], s[40:41]
	s_cbranch_execz .LBB0_902
	v_pk_fma_f32 v[76:77], v[76:77], v[128:129], v[132:133]
	v_pk_fma_f32 v[78:79], v[78:79], v[130:131], v[134:135]
	v_pk_fma_f32 v[76:77], v[120:121], v[84:85], v[76:77]
	v_pk_fma_f32 v[78:79], v[122:123], v[86:87], v[78:79]
	v_pk_fma_f32 v[76:77], v[116:117], v[80:81], v[76:77]
	v_pk_fma_f32 v[78:79], v[118:119], v[82:83], v[78:79]
	v_mul_f32_e32 v80, 0x3d372713, v77
	v_mul_f32_e32 v80, v77, v80
	v_mul_f32_e32 v81, 0x3d372713, v76
	v_fma_f32 v80, v77, v80, v77
	v_mul_f32_e32 v81, v76, v81
	v_mul_f32_e32 v80, 0xc0135761, v80
	v_fma_f32 v81, v76, v81, v76
	v_exp_f32_e32 v80, v80
	v_mul_f32_e32 v81, 0xc0135761, v81
	v_mul_f32_e32 v82, 0x3d372713, v79
	v_exp_f32_e32 v84, v81
	v_mul_f32_e32 v82, v79, v82
	v_mul_f32_e32 v83, 0x3d372713, v78
	v_fma_f32 v82, v79, v82, v79
	v_mul_f32_e32 v83, v78, v83
	v_mul_f32_e32 v82, 0xc0135761, v82
	v_fma_f32 v83, v78, v83, v78
	v_add_f32_e32 v80, 1.0, v80
	v_exp_f32_e32 v82, v82
	v_mul_f32_e32 v83, 0xc0135761, v83
	v_rcp_f32_e32 v81, v80
	v_add_f32_e32 v80, 1.0, v84
	v_exp_f32_e32 v84, v83
	v_add_f32_e32 v82, 1.0, v82
	v_rcp_f32_e32 v80, v80
	v_rcp_f32_e32 v83, v82
	v_add_f32_e32 v82, 1.0, v84
	v_rcp_f32_e32 v82, v82
	v_pk_mul_f32 v[76:77], v[76:77], v[80:81]
	v_pk_mul_f32 v[72:73], v[72:73], v[76:77]
	v_pk_mul_f32 v[76:77], v[78:79], v[82:83]
	v_pk_mul_f32 v[74:75], v[74:75], v[76:77]
	v_cvt_pk_bf16_f32 v228, v72, v73
	v_cvt_pk_bf16_f32 v229, v74, v75
.LBB0_902:
	s_or_b64 exec, exec, s[6:7]
	v_add_u32_e32 v80, 0xb0, v190
	v_add_u32_e32 v81, s21, v80
	v_max_i32_e32 v82, 0, v81
	v_mul_hi_u32 v83, v82, s64
	v_add_u32_e32 v94, s58, v188
	v_add_u32_e32 v95, v94, v187
	ds_read_b128 v[76:79], v94 offset:10752
	ds_read_b128 v[72:75], v95 offset:10240
	v_lshrrev_b32_e32 v83, 11, v83
	v_mul_i32_i24_e32 v84, 0xffffeff0, v83
	v_add_u32_e32 v82, v84, v82
	v_cmp_lt_i32_e32 vcc, 1, v80
	v_cmp_lt_i32_e64 s[8:9], 15, v82
	v_cmp_gt_i32_e64 s[6:7], s65, v81
	s_and_b64 s[8:9], vcc, s[8:9]
	s_waitcnt lgkmcnt(0)
	v_mov_b32_dpp v76, v68 row_shr:1 row_mask:0xf bank_mask:0xf
	v_mov_b32_dpp v72, v68 row_shr:2 row_mask:0xf bank_mask:0xf
	v_mov_b32_dpp v77, v69 row_shr:1 row_mask:0xf bank_mask:0xf
	v_mov_b32_dpp v73, v69 row_shr:2 row_mask:0xf bank_mask:0xf
	v_mov_b32_dpp v78, v70 row_shr:1 row_mask:0xf bank_mask:0xf
	v_mov_b32_dpp v74, v70 row_shr:2 row_mask:0xf bank_mask:0xf
	v_mov_b32_dpp v79, v71 row_shr:1 row_mask:0xf bank_mask:0xf
	v_mov_b32_dpp v75, v71 row_shr:2 row_mask:0xf bank_mask:0xf
	s_and_b64 s[6:7], s[8:9], s[6:7]
	v_lshl_add_u32 v91, v83, 12, v82
	s_and_saveexec_b64 s[8:9], s[6:7]
	s_cbranch_execz .LBB0_904
	v_pk_fma_f32 v[68:69], v[68:69], v[128:129], v[132:133]
	v_pk_fma_f32 v[70:71], v[70:71], v[130:131], v[134:135]
	v_pk_fma_f32 v[68:69], v[120:121], v[76:77], v[68:69]
	v_pk_fma_f32 v[70:71], v[122:123], v[78:79], v[70:71]
	v_pk_fma_f32 v[68:69], v[116:117], v[72:73], v[68:69]
	v_pk_fma_f32 v[70:71], v[118:119], v[74:75], v[70:71]
	v_mul_f32_e32 v72, 0x3d372713, v69
	v_mul_f32_e32 v72, v69, v72
	v_mul_f32_e32 v73, 0x3d372713, v68
	v_fma_f32 v72, v69, v72, v69
	v_mul_f32_e32 v73, v68, v73
	v_mul_f32_e32 v72, 0xc0135761, v72
	v_fma_f32 v73, v68, v73, v68
	v_exp_f32_e32 v72, v72
	v_mul_f32_e32 v73, 0xc0135761, v73
	v_mul_f32_e32 v74, 0x3d372713, v71
	v_exp_f32_e32 v76, v73
	v_mul_f32_e32 v74, v71, v74
	v_mul_f32_e32 v75, 0x3d372713, v70
	v_fma_f32 v74, v71, v74, v71
	v_mul_f32_e32 v75, v70, v75
	v_mul_f32_e32 v74, 0xc0135761, v74
	v_fma_f32 v75, v70, v75, v70
	v_add_f32_e32 v72, 1.0, v72
	v_exp_f32_e32 v74, v74
	v_mul_f32_e32 v75, 0xc0135761, v75
	v_rcp_f32_e32 v73, v72
	v_add_f32_e32 v72, 1.0, v76
	v_exp_f32_e32 v76, v75
	v_add_f32_e32 v74, 1.0, v74
	v_rcp_f32_e32 v72, v72
	v_rcp_f32_e32 v75, v74
	v_add_f32_e32 v74, 1.0, v76
	v_rcp_f32_e32 v74, v74
	v_pk_mul_f32 v[68:69], v[68:69], v[72:73]
	v_pk_mul_f32 v[60:61], v[60:61], v[68:69]
	v_pk_mul_f32 v[68:69], v[70:71], v[74:75]
	v_pk_mul_f32 v[62:63], v[62:63], v[68:69]
	v_cvt_pk_bf16_f32 v232, v60, v61
	v_cvt_pk_bf16_f32 v233, v62, v63
; #define LAS __attribute__((address_space(3)))
; __device__ __forceinline__ unsigned pk2e(float lo, float hi) { typedef __bf16 b2 __attribute__((ext_vector_type(2))); b2 v; v.x = (__bf16)lo; v.y = (__bf16)hi; return __builtin_bit_cast(unsigned, v); }
; __device__ __forceinline__ float ex2(float x) { return __builtin_amdgcn_exp2f(x); }
;     __device__ __forceinline__ void operator()(const f32x4 (&acc)[2][2][4][2], const Unit& u, int wr, int wc, int fr, int fq, LAS unsigned char* hb) const {
;     ...
;             const int c4 = ch + 4 * n;
;             const f32x4 w0 = *(const f32x4*)(cw + 0 * DFF + c4), w1 = *(const f32x4*)(cw + 1 * DFF + c4), w2 = *(const f32x4*)(cw + 2 * DFF + c4), bs = *(const f32x4*)(cb + c4);
; #pragma unroll
;             for (int ai = 0; ai < 2; ++ai)
; #pragma unroll
;                 for (int m = 0; m < 4; ++m) { const int q = 8 * ai + 4 * wr + m, prev = q > 0 ? q - 1 : 0; const int lr = ai * HALF + wr * 64 + m * 16 + fr, R = R0 + lr;
;                     const int Rc = R < 0 ? 0 : R; const int b = Rc / LL, p = Rc - b * LL;
;                     const LAS unsigned char* hp = hb + (prev * H * NCH + chl + 4 * n) * 4;
;                     const f32x4 h1 = *(const LAS f32x4*)(hp + hr1 * NCH * 4), h2 = *(const LAS f32x4*)(hp + hr2 * NCH * 4);
;                     const f32x4 gv = acc[ai][0][m][n], uv = acc[ai][1][m][n];
;                     float o[4];
; #pragma unroll
;                     for (int j = 0; j < 4; ++j) { const float g = gv[j];
;                         float g1 = dpp_row_shr<1>(h1[j], g), g2 = dpp_row_shr<2>(h2[j], g);
;                         g1 = p >= 1 ? g1 : 0.f; g2 = p >= 2 ? g2 : 0.f;
;                         const float v = bs[j] + w2[j] * g + w1[j] * g1 + w0[j] * g2;
;                         const float a = v + 0.044715f * v * v * v;
;                         const float ge = v * __builtin_amdgcn_rcpf(1.f + ex2(-2.f * 0.7978845608028654f * 1.4426950408889634f * a));
;                         o[j] = ge * uv[j]; }
;                     if (lr >= H && R < TT && p >= NMETA) { u32x2 w; w.x = pk2e(o[0], o[1]); w.y = pk2e(o[2], o[3]);
;                         *(u32x2*)(ACT + ((size_t)b * SEQ + p - NMETA) * DFF + c4) = w; } }
.LBB0_904:
	s_or_b64 exec, exec, s[8:9]
	global_load_dwordx4 v[60:63], v[172:173], off offset:16
	global_load_dwordx4 v[68:71], v[174:175], off offset:16
	global_load_dwordx4 v[72:75], v[176:177], off offset:16
	global_load_dwordx4 v[76:79], v[178:179], off offset:16
	v_add_u32_e32 v99, 0xfffffc10, v188
	v_add_u32_e32 v80, s51, v99
	v_add_u32_e32 v81, v80, v187
	ds_read_b128 v[84:87], v80 offset:512
	ds_read_b128 v[80:83], v81
	v_add_u32_e32 v88, 4, v170
	v_ashrrev_i32_e32 v89, 31, v88
	s_waitcnt lgkmcnt(0)
	v_mov_b32_dpp v84, v64 row_shr:1 row_mask:0xf bank_mask:0xf
	v_mov_b32_dpp v80, v64 row_shr:2 row_mask:0xf bank_mask:0xf
	v_mov_b32_dpp v85, v65 row_shr:1 row_mask:0xf bank_mask:0xf
	v_mov_b32_dpp v81, v65 row_shr:2 row_mask:0xf bank_mask:0xf
	v_mov_b32_dpp v86, v66 row_shr:1 row_mask:0xf bank_mask:0xf
	v_mov_b32_dpp v82, v66 row_shr:2 row_mask:0xf bank_mask:0xf
	v_mov_b32_dpp v87, v67 row_shr:1 row_mask:0xf bank_mask:0xf
	v_mov_b32_dpp v83, v67 row_shr:2 row_mask:0xf bank_mask:0xf
	s_waitcnt vmcnt(0)
	s_and_saveexec_b64 s[8:9], s[26:27]
	s_cbranch_execz .LBB0_906
	v_pk_fma_f32 v[64:65], v[64:65], v[72:73], v[76:77]
	v_pk_fma_f32 v[66:67], v[66:67], v[74:75], v[78:79]
	v_pk_fma_f32 v[64:65], v[68:69], v[84:85], v[64:65]
	v_pk_fma_f32 v[66:67], v[70:71], v[86:87], v[66:67]
	v_pk_fma_f32 v[64:65], v[60:61], v[80:81], v[64:65]
	v_pk_fma_f32 v[66:67], v[62:63], v[82:83], v[66:67]
	v_mul_f32_e32 v80, 0x3d372713, v65
	v_mul_f32_e32 v80, v65, v80
	v_mul_f32_e32 v81, 0x3d372713, v64
	v_fma_f32 v80, v65, v80, v65
	v_mul_f32_e32 v81, v64, v81
	v_mul_f32_e32 v80, 0xc0135761, v80
	v_fma_f32 v81, v64, v81, v64
	v_exp_f32_e32 v80, v80
	v_mul_f32_e32 v81, 0xc0135761, v81
	v_mul_f32_e32 v82, 0x3d372713, v67
	v_exp_f32_e32 v84, v81
	v_mul_f32_e32 v82, v67, v82
	v_mul_f32_e32 v83, 0x3d372713, v66
	v_fma_f32 v82, v67, v82, v67
	v_mul_f32_e32 v83, v66, v83
	v_mul_f32_e32 v82, 0xc0135761, v82
	v_fma_f32 v83, v66, v83, v66
	v_add_f32_e32 v80, 1.0, v80
	v_exp_f32_e32 v82, v82
	v_mul_f32_e32 v83, 0xc0135761, v83
	v_rcp_f32_e32 v81, v80
	v_add_f32_e32 v80, 1.0, v84
	v_exp_f32_e32 v84, v83
	v_add_f32_e32 v82, 1.0, v82
	v_rcp_f32_e32 v80, v80
	v_rcp_f32_e32 v83, v82
	v_add_f32_e32 v82, 1.0, v84
	v_rcp_f32_e32 v82, v82
	v_pk_mul_f32 v[64:65], v[64:65], v[80:81]
	v_readlane_b32 s12, v237, 50
	v_pk_mul_f32 v[56:57], v[56:57], v[64:65]
	v_pk_mul_f32 v[64:65], v[66:67], v[82:83]
	v_readlane_b32 s13, v237, 51
	v_pk_mul_f32 v[58:59], v[58:59], v[64:65]
	v_cvt_pk_bf16_f32 v198, v56, v57
	v_cvt_pk_bf16_f32 v199, v58, v59
	v_mov_b64_e32 v[58:59], s[12:13]
	v_mad_u64_u32 v[58:59], s[26:27], v189, s66, v[58:59]
	v_lshl_add_u64 v[58:59], v[88:89], 1, v[58:59]
	v_add_co_u32_e32 v58, vcc, 0xfffea000, v58
	s_nop 1
	v_addc_co_u32_e32 v59, vcc, -1, v59, vcc
	global_store_dwordx4 v[58:59], v[196:199], off offset:-8
.LBB0_906:
	s_or_b64 exec, exec, s[8:9]
	v_add_u32_e32 v56, s52, v99
	ds_read_b128 v[64:67], v56 offset:512
	v_add_u32_e32 v56, v56, v187
	ds_read_b128 v[56:59], v56
	s_waitcnt lgkmcnt(0)
	v_mov_b32_dpp v64, v52 row_shr:1 row_mask:0xf bank_mask:0xf
	v_mov_b32_dpp v65, v53 row_shr:1 row_mask:0xf bank_mask:0xf
	v_mov_b32_dpp v56, v52 row_shr:2 row_mask:0xf bank_mask:0xf
	v_mov_b32_dpp v57, v53 row_shr:2 row_mask:0xf bank_mask:0xf
	v_mov_b32_dpp v66, v54 row_shr:1 row_mask:0xf bank_mask:0xf
	v_mov_b32_dpp v58, v54 row_shr:2 row_mask:0xf bank_mask:0xf
	v_mov_b32_dpp v67, v55 row_shr:1 row_mask:0xf bank_mask:0xf
	v_mov_b32_dpp v59, v55 row_shr:2 row_mask:0xf bank_mask:0xf
	s_and_saveexec_b64 s[8:9], s[28:29]
	s_cbranch_execz .LBB0_908
	v_pk_fma_f32 v[52:53], v[52:53], v[72:73], v[76:77]
	v_pk_fma_f32 v[54:55], v[54:55], v[74:75], v[78:79]
	v_pk_fma_f32 v[52:53], v[68:69], v[64:65], v[52:53]
	v_pk_fma_f32 v[54:55], v[70:71], v[66:67], v[54:55]
	v_pk_fma_f32 v[52:53], v[60:61], v[56:57], v[52:53]
	v_pk_fma_f32 v[54:55], v[62:63], v[58:59], v[54:55]
	v_mul_f32_e32 v56, 0x3d372713, v53
	v_mul_f32_e32 v56, v53, v56
	v_mul_f32_e32 v57, 0x3d372713, v52
	v_fma_f32 v56, v53, v56, v53
	v_mul_f32_e32 v57, v52, v57
	v_mul_f32_e32 v56, 0xc0135761, v56
	v_fma_f32 v57, v52, v57, v52
	v_exp_f32_e32 v56, v56
	v_mul_f32_e32 v57, 0xc0135761, v57
	v_mul_f32_e32 v58, 0x3d372713, v55
	v_exp_f32_e32 v64, v57
	v_mul_f32_e32 v58, v55, v58
	v_mul_f32_e32 v59, 0x3d372713, v54
	v_fma_f32 v58, v55, v58, v55
	v_mul_f32_e32 v59, v54, v59
	v_mul_f32_e32 v58, 0xc0135761, v58
	v_fma_f32 v59, v54, v59, v54
	v_add_f32_e32 v56, 1.0, v56
	v_exp_f32_e32 v58, v58
	v_mul_f32_e32 v59, 0xc0135761, v59
	v_rcp_f32_e32 v57, v56
	v_add_f32_e32 v56, 1.0, v64
	v_exp_f32_e32 v64, v59
	v_add_f32_e32 v58, 1.0, v58
	v_rcp_f32_e32 v56, v56
	v_rcp_f32_e32 v59, v58
	v_add_f32_e32 v58, 1.0, v64
	v_rcp_f32_e32 v58, v58
	v_pk_mul_f32 v[52:53], v[52:53], v[56:57]
	v_readlane_b32 s12, v237, 50
	v_pk_mul_f32 v[48:49], v[48:49], v[52:53]
	v_pk_mul_f32 v[52:53], v[54:55], v[58:59]
	v_readlane_b32 s13, v237, 51
	v_pk_mul_f32 v[50:51], v[50:51], v[52:53]
	v_cvt_pk_bf16_f32 v202, v48, v49
	v_cvt_pk_bf16_f32 v203, v50, v51
	v_mov_b64_e32 v[50:51], s[12:13]
	v_mad_u64_u32 v[50:51], s[26:27], v144, s66, v[50:51]
	v_lshl_add_u64 v[50:51], v[88:89], 1, v[50:51]
	v_add_co_u32_e32 v50, vcc, 0xfffea000, v50
	s_nop 1
	v_addc_co_u32_e32 v51, vcc, -1, v51, vcc
	global_store_dwordx4 v[50:51], v[200:203], off offset:-8
; #define LAS __attribute__((address_space(3)))
; __device__ __forceinline__ unsigned pk2e(float lo, float hi) { typedef __bf16 b2 __attribute__((ext_vector_type(2))); b2 v; v.x = (__bf16)lo; v.y = (__bf16)hi; return __builtin_bit_cast(unsigned, v); }
; __device__ __forceinline__ float ex2(float x) { return __builtin_amdgcn_exp2f(x); }
;     __device__ __forceinline__ void operator()(const f32x4 (&acc)[2][2][4][2], const Unit& u, int wr, int wc, int fr, int fq, LAS unsigned char* hb) const {
;     ...
;                 for (int m = 0; m < 4; ++m) { const int q = 8 * ai + 4 * wr + m, prev = q > 0 ? q - 1 : 0; const int lr = ai * HALF + wr * 64 + m * 16 + fr, R = R0 + lr;
;                     const int Rc = R < 0 ? 0 : R; const int b = Rc / LL, p = Rc - b * LL;
;                     const LAS unsigned char* hp = hb + (prev * H * NCH + chl + 4 * n) * 4;
;                     const f32x4 h1 = *(const LAS f32x4*)(hp + hr1 * NCH * 4), h2 = *(const LAS f32x4*)(hp + hr2 * NCH * 4);
;                     const f32x4 gv = acc[ai][0][m][n], uv = acc[ai][1][m][n];
;                     float o[4];
; #pragma unroll
;                     for (int j = 0; j < 4; ++j) { const float g = gv[j];
;                         float g1 = dpp_row_shr<1>(h1[j], g), g2 = dpp_row_shr<2>(h2[j], g);
;                         g1 = p >= 1 ? g1 : 0.f; g2 = p >= 2 ? g2 : 0.f;
;                         const float v = bs[j] + w2[j] * g + w1[j] * g1 + w0[j] * g2;
;                         const float a = v + 0.044715f * v * v * v;
;                         const float ge = v * __builtin_amdgcn_rcpf(1.f + ex2(-2.f * 0.7978845608028654f * 1.4426950408889634f * a));
;                         o[j] = ge * uv[j]; }
;                     if (lr >= H && R < TT && p >= NMETA) { u32x2 w; w.x = pk2e(o[0], o[1]); w.y = pk2e(o[2], o[3]);
;                         *(u32x2*)(ACT + ((size_t)b * SEQ + p - NMETA) * DFF + c4) = w; } }
.LBB0_908:
	s_or_b64 exec, exec, s[8:9]
	v_add_u32_e32 v48, s53, v99
	ds_read_b128 v[52:55], v48 offset:512
	v_add_u32_e32 v48, v48, v187
	ds_read_b128 v[48:51], v48
	s_waitcnt lgkmcnt(0)
	v_mov_b32_dpp v52, v44 row_shr:1 row_mask:0xf bank_mask:0xf
	v_mov_b32_dpp v53, v45 row_shr:1 row_mask:0xf bank_mask:0xf
	v_mov_b32_dpp v48, v44 row_shr:2 row_mask:0xf bank_mask:0xf
	v_mov_b32_dpp v49, v45 row_shr:2 row_mask:0xf bank_mask:0xf
	v_mov_b32_dpp v54, v46 row_shr:1 row_mask:0xf bank_mask:0xf
	v_mov_b32_dpp v50, v46 row_shr:2 row_mask:0xf bank_mask:0xf
	v_mov_b32_dpp v55, v47 row_shr:1 row_mask:0xf bank_mask:0xf
	v_mov_b32_dpp v51, v47 row_shr:2 row_mask:0xf bank_mask:0xf
	s_and_saveexec_b64 s[8:9], s[30:31]
	s_cbranch_execz .LBB0_910
	v_pk_fma_f32 v[44:45], v[44:45], v[72:73], v[76:77]
	v_pk_fma_f32 v[46:47], v[46:47], v[74:75], v[78:79]
	v_pk_fma_f32 v[44:45], v[68:69], v[52:53], v[44:45]
	v_pk_fma_f32 v[46:47], v[70:71], v[54:55], v[46:47]
	v_pk_fma_f32 v[44:45], v[60:61], v[48:49], v[44:45]
	v_pk_fma_f32 v[46:47], v[62:63], v[50:51], v[46:47]
	v_mul_f32_e32 v48, 0x3d372713, v45
	v_mul_f32_e32 v48, v45, v48
	v_mul_f32_e32 v49, 0x3d372713, v44
	v_fma_f32 v48, v45, v48, v45
	v_mul_f32_e32 v49, v44, v49
	v_mul_f32_e32 v48, 0xc0135761, v48
	v_fma_f32 v49, v44, v49, v44
	v_exp_f32_e32 v48, v48
	v_mul_f32_e32 v49, 0xc0135761, v49
	v_mul_f32_e32 v50, 0x3d372713, v47
	v_exp_f32_e32 v52, v49
	v_mul_f32_e32 v50, v47, v50
	v_mul_f32_e32 v51, 0x3d372713, v46
	v_fma_f32 v50, v47, v50, v47
	v_mul_f32_e32 v51, v46, v51
	v_mul_f32_e32 v50, 0xc0135761, v50
	v_fma_f32 v51, v46, v51, v46
	v_add_f32_e32 v48, 1.0, v48
	v_exp_f32_e32 v50, v50
	v_mul_f32_e32 v51, 0xc0135761, v51
	v_rcp_f32_e32 v49, v48
	v_add_f32_e32 v48, 1.0, v52
	v_exp_f32_e32 v52, v51
	v_add_f32_e32 v50, 1.0, v50
	v_rcp_f32_e32 v48, v48
	v_rcp_f32_e32 v51, v50
	v_add_f32_e32 v50, 1.0, v52
	v_rcp_f32_e32 v50, v50
	v_pk_mul_f32 v[44:45], v[44:45], v[48:49]
	v_readlane_b32 s12, v237, 50
	v_pk_mul_f32 v[40:41], v[40:41], v[44:45]
	v_pk_mul_f32 v[44:45], v[46:47], v[50:51]
	v_readlane_b32 s13, v237, 51
	v_pk_mul_f32 v[42:43], v[42:43], v[44:45]
	v_cvt_pk_bf16_f32 v206, v40, v41
	v_cvt_pk_bf16_f32 v207, v42, v43
	v_mov_b64_e32 v[42:43], s[12:13]
	v_mad_u64_u32 v[42:43], s[26:27], v136, s66, v[42:43]
	v_lshl_add_u64 v[42:43], v[88:89], 1, v[42:43]
	v_add_co_u32_e32 v42, vcc, 0xfffea000, v42
	s_nop 1
	v_addc_co_u32_e32 v43, vcc, -1, v43, vcc
	global_store_dwordx4 v[42:43], v[204:207], off offset:-8
.LBB0_910:
	s_or_b64 exec, exec, s[8:9]
	v_add_u32_e32 v40, s54, v99
	ds_read_b128 v[44:47], v40 offset:512
	v_add_u32_e32 v40, v40, v187
	ds_read_b128 v[40:43], v40
	s_waitcnt lgkmcnt(0)
	v_mov_b32_dpp v44, v36 row_shr:1 row_mask:0xf bank_mask:0xf
	v_mov_b32_dpp v45, v37 row_shr:1 row_mask:0xf bank_mask:0xf
	v_mov_b32_dpp v40, v36 row_shr:2 row_mask:0xf bank_mask:0xf
	v_mov_b32_dpp v41, v37 row_shr:2 row_mask:0xf bank_mask:0xf
	v_mov_b32_dpp v46, v38 row_shr:1 row_mask:0xf bank_mask:0xf
	v_mov_b32_dpp v42, v38 row_shr:2 row_mask:0xf bank_mask:0xf
	v_mov_b32_dpp v47, v39 row_shr:1 row_mask:0xf bank_mask:0xf
	v_mov_b32_dpp v43, v39 row_shr:2 row_mask:0xf bank_mask:0xf
	s_and_saveexec_b64 s[8:9], s[34:35]
	s_cbranch_execz .LBB0_912
	v_pk_fma_f32 v[36:37], v[36:37], v[72:73], v[76:77]
	v_pk_fma_f32 v[38:39], v[38:39], v[74:75], v[78:79]
	v_pk_fma_f32 v[36:37], v[68:69], v[44:45], v[36:37]
	v_pk_fma_f32 v[38:39], v[70:71], v[46:47], v[38:39]
	v_pk_fma_f32 v[36:37], v[60:61], v[40:41], v[36:37]
	v_pk_fma_f32 v[38:39], v[62:63], v[42:43], v[38:39]
	v_mul_f32_e32 v40, 0x3d372713, v37
	v_mul_f32_e32 v40, v37, v40
	v_mul_f32_e32 v41, 0x3d372713, v36
	v_fma_f32 v40, v37, v40, v37
	v_mul_f32_e32 v41, v36, v41
	v_mul_f32_e32 v40, 0xc0135761, v40
	v_fma_f32 v41, v36, v41, v36
	v_exp_f32_e32 v40, v40
	v_mul_f32_e32 v41, 0xc0135761, v41
	v_mul_f32_e32 v42, 0x3d372713, v39
	v_exp_f32_e32 v44, v41
	v_mul_f32_e32 v42, v39, v42
	v_mul_f32_e32 v43, 0x3d372713, v38
	v_fma_f32 v42, v39, v42, v39
	v_mul_f32_e32 v43, v38, v43
	v_mul_f32_e32 v42, 0xc0135761, v42
	v_fma_f32 v43, v38, v43, v38
	v_add_f32_e32 v40, 1.0, v40
	v_exp_f32_e32 v42, v42
	v_mul_f32_e32 v43, 0xc0135761, v43
	v_rcp_f32_e32 v41, v40
	v_add_f32_e32 v40, 1.0, v44
	v_exp_f32_e32 v44, v43
	v_add_f32_e32 v42, 1.0, v42
	v_rcp_f32_e32 v40, v40
	v_rcp_f32_e32 v43, v42
	v_add_f32_e32 v42, 1.0, v44
	v_rcp_f32_e32 v42, v42
	v_pk_mul_f32 v[36:37], v[36:37], v[40:41]
	v_readlane_b32 s12, v237, 50
	v_pk_mul_f32 v[32:33], v[32:33], v[36:37]
	v_pk_mul_f32 v[36:37], v[38:39], v[42:43]
	v_readlane_b32 s13, v237, 51
	v_pk_mul_f32 v[34:35], v[34:35], v[36:37]
	v_cvt_pk_bf16_f32 v210, v32, v33
	v_cvt_pk_bf16_f32 v211, v34, v35
	v_mov_b64_e32 v[34:35], s[12:13]
	v_mad_u64_u32 v[34:35], s[26:27], v112, s66, v[34:35]
	v_lshl_add_u64 v[34:35], v[88:89], 1, v[34:35]
	v_add_co_u32_e32 v34, vcc, 0xfffea000, v34
	s_nop 1
	v_addc_co_u32_e32 v35, vcc, -1, v35, vcc
	global_store_dwordx4 v[34:35], v[208:211], off offset:-8
; #define LAS __attribute__((address_space(3)))
; __device__ __forceinline__ unsigned pk2e(float lo, float hi) { typedef __bf16 b2 __attribute__((ext_vector_type(2))); b2 v; v.x = (__bf16)lo; v.y = (__bf16)hi; return __builtin_bit_cast(unsigned, v); }
; __device__ __forceinline__ float ex2(float x) { return __builtin_amdgcn_exp2f(x); }
;     __device__ __forceinline__ void operator()(const f32x4 (&acc)[2][2][4][2], const Unit& u, int wr, int wc, int fr, int fq, LAS unsigned char* hb) const {
;     ...
;                 for (int m = 0; m < 4; ++m) { const int q = 8 * ai + 4 * wr + m, prev = q > 0 ? q - 1 : 0; const int lr = ai * HALF + wr * 64 + m * 16 + fr, R = R0 + lr;
;                     const int Rc = R < 0 ? 0 : R; const int b = Rc / LL, p = Rc - b * LL;
;                     const LAS unsigned char* hp = hb + (prev * H * NCH + chl + 4 * n) * 4;
;                     const f32x4 h1 = *(const LAS f32x4*)(hp + hr1 * NCH * 4), h2 = *(const LAS f32x4*)(hp + hr2 * NCH * 4);
;                     const f32x4 gv = acc[ai][0][m][n], uv = acc[ai][1][m][n];
;                     float o[4];
; #pragma unroll
;                     for (int j = 0; j < 4; ++j) { const float g = gv[j];
;                         float g1 = dpp_row_shr<1>(h1[j], g), g2 = dpp_row_shr<2>(h2[j], g);
;                         g1 = p >= 1 ? g1 : 0.f; g2 = p >= 2 ? g2 : 0.f;
;                         const float v = bs[j] + w2[j] * g + w1[j] * g1 + w0[j] * g2;
;                         const float a = v + 0.044715f * v * v * v;
;                         const float ge = v * __builtin_amdgcn_rcpf(1.f + ex2(-2.f * 0.7978845608028654f * 1.4426950408889634f * a));
;                         o[j] = ge * uv[j]; }
;                     if (lr >= H && R < TT && p >= NMETA) { u32x2 w; w.x = pk2e(o[0], o[1]); w.y = pk2e(o[2], o[3]);
;                         *(u32x2*)(ACT + ((size_t)b * SEQ + p - NMETA) * DFF + c4) = w; } }
.LBB0_912:
	s_or_b64 exec, exec, s[8:9]
	ds_read_b128 v[36:39], v105 offset:7696
	ds_read_b128 v[32:35], v106 offset:7184
	s_waitcnt lgkmcnt(0)
	v_mov_b32_dpp v36, v28 row_shr:1 row_mask:0xf bank_mask:0xf
	v_mov_b32_dpp v32, v28 row_shr:2 row_mask:0xf bank_mask:0xf
	v_mov_b32_dpp v37, v29 row_shr:1 row_mask:0xf bank_mask:0xf
	v_mov_b32_dpp v33, v29 row_shr:2 row_mask:0xf bank_mask:0xf
	v_mov_b32_dpp v38, v30 row_shr:1 row_mask:0xf bank_mask:0xf
	v_mov_b32_dpp v34, v30 row_shr:2 row_mask:0xf bank_mask:0xf
	v_mov_b32_dpp v39, v31 row_shr:1 row_mask:0xf bank_mask:0xf
	v_mov_b32_dpp v35, v31 row_shr:2 row_mask:0xf bank_mask:0xf
	s_and_saveexec_b64 s[8:9], s[36:37]
	s_cbranch_execz .LBB0_914
	v_pk_fma_f32 v[28:29], v[28:29], v[72:73], v[76:77]
	v_pk_fma_f32 v[30:31], v[30:31], v[74:75], v[78:79]
	v_pk_fma_f32 v[28:29], v[68:69], v[36:37], v[28:29]
	v_pk_fma_f32 v[30:31], v[70:71], v[38:39], v[30:31]
	v_pk_fma_f32 v[28:29], v[60:61], v[32:33], v[28:29]
	v_pk_fma_f32 v[30:31], v[62:63], v[34:35], v[30:31]
	v_mul_f32_e32 v32, 0x3d372713, v29
	v_mul_f32_e32 v32, v29, v32
	v_mul_f32_e32 v33, 0x3d372713, v28
	v_fma_f32 v32, v29, v32, v29
	v_mul_f32_e32 v33, v28, v33
	v_mul_f32_e32 v32, 0xc0135761, v32
	v_fma_f32 v33, v28, v33, v28
	v_exp_f32_e32 v32, v32
	v_mul_f32_e32 v33, 0xc0135761, v33
	v_mul_f32_e32 v34, 0x3d372713, v31
	v_exp_f32_e32 v36, v33
	v_mul_f32_e32 v34, v31, v34
	v_mul_f32_e32 v35, 0x3d372713, v30
	v_fma_f32 v34, v31, v34, v31
	v_mul_f32_e32 v35, v30, v35
	v_mul_f32_e32 v34, 0xc0135761, v34
	v_fma_f32 v35, v30, v35, v30
	v_add_f32_e32 v32, 1.0, v32
	v_exp_f32_e32 v34, v34
	v_mul_f32_e32 v35, 0xc0135761, v35
	v_rcp_f32_e32 v33, v32
	v_add_f32_e32 v32, 1.0, v36
	v_exp_f32_e32 v36, v35
	v_add_f32_e32 v34, 1.0, v34
	v_rcp_f32_e32 v32, v32
	v_rcp_f32_e32 v35, v34
	v_add_f32_e32 v34, 1.0, v36
	v_rcp_f32_e32 v34, v34
	v_pk_mul_f32 v[28:29], v[28:29], v[32:33]
	v_readlane_b32 s12, v237, 50
	v_pk_mul_f32 v[24:25], v[24:25], v[28:29]
	v_pk_mul_f32 v[28:29], v[30:31], v[34:35]
	v_readlane_b32 s13, v237, 51
	v_pk_mul_f32 v[26:27], v[26:27], v[28:29]
	v_cvt_pk_bf16_f32 v214, v24, v25
	v_cvt_pk_bf16_f32 v215, v26, v27
	v_mov_b64_e32 v[26:27], s[12:13]
	v_mad_u64_u32 v[26:27], s[26:27], v104, s66, v[26:27]
	v_lshl_add_u64 v[26:27], v[88:89], 1, v[26:27]
	v_add_co_u32_e32 v26, vcc, 0xfffea000, v26
	s_nop 1
	v_addc_co_u32_e32 v27, vcc, -1, v27, vcc
	global_store_dwordx4 v[26:27], v[212:215], off offset:-8
.LBB0_914:
	s_or_b64 exec, exec, s[8:9]
	ds_read_b128 v[28:31], v97 offset:8720
	ds_read_b128 v[24:27], v98 offset:8208
	s_waitcnt lgkmcnt(0)
	v_mov_b32_dpp v28, v20 row_shr:1 row_mask:0xf bank_mask:0xf
	v_mov_b32_dpp v24, v20 row_shr:2 row_mask:0xf bank_mask:0xf
	v_mov_b32_dpp v29, v21 row_shr:1 row_mask:0xf bank_mask:0xf
	v_mov_b32_dpp v25, v21 row_shr:2 row_mask:0xf bank_mask:0xf
	v_mov_b32_dpp v30, v22 row_shr:1 row_mask:0xf bank_mask:0xf
	v_mov_b32_dpp v26, v22 row_shr:2 row_mask:0xf bank_mask:0xf
	v_mov_b32_dpp v31, v23 row_shr:1 row_mask:0xf bank_mask:0xf
	v_mov_b32_dpp v27, v23 row_shr:2 row_mask:0xf bank_mask:0xf
	s_and_saveexec_b64 s[8:9], s[38:39]
	s_cbranch_execz .LBB0_916
	v_pk_fma_f32 v[20:21], v[20:21], v[72:73], v[76:77]
	v_pk_fma_f32 v[22:23], v[22:23], v[74:75], v[78:79]
	v_pk_fma_f32 v[20:21], v[68:69], v[28:29], v[20:21]
	v_pk_fma_f32 v[22:23], v[70:71], v[30:31], v[22:23]
	v_pk_fma_f32 v[20:21], v[60:61], v[24:25], v[20:21]
	v_pk_fma_f32 v[22:23], v[62:63], v[26:27], v[22:23]
	v_mul_f32_e32 v24, 0x3d372713, v21
	v_mul_f32_e32 v24, v21, v24
	v_mul_f32_e32 v25, 0x3d372713, v20
	v_fma_f32 v24, v21, v24, v21
	v_mul_f32_e32 v25, v20, v25
	v_mul_f32_e32 v24, 0xc0135761, v24
	v_fma_f32 v25, v20, v25, v20
	v_exp_f32_e32 v24, v24
	v_mul_f32_e32 v25, 0xc0135761, v25
	v_mul_f32_e32 v26, 0x3d372713, v23
	v_exp_f32_e32 v28, v25
	v_mul_f32_e32 v26, v23, v26
	v_mul_f32_e32 v27, 0x3d372713, v22
	v_fma_f32 v26, v23, v26, v23
	v_mul_f32_e32 v27, v22, v27
	v_mul_f32_e32 v26, 0xc0135761, v26
	v_fma_f32 v27, v22, v27, v22
	v_add_f32_e32 v24, 1.0, v24
	v_exp_f32_e32 v26, v26
	v_mul_f32_e32 v27, 0xc0135761, v27
	v_rcp_f32_e32 v25, v24
	v_add_f32_e32 v24, 1.0, v28
	v_exp_f32_e32 v28, v27
	v_add_f32_e32 v26, 1.0, v26
	v_rcp_f32_e32 v24, v24
	v_rcp_f32_e32 v27, v26
	v_add_f32_e32 v26, 1.0, v28
	v_rcp_f32_e32 v26, v26
	v_pk_mul_f32 v[20:21], v[20:21], v[24:25]
	v_readlane_b32 s12, v237, 50
	v_pk_mul_f32 v[16:17], v[16:17], v[20:21]
	v_pk_mul_f32 v[20:21], v[22:23], v[26:27]
	v_readlane_b32 s13, v237, 51
	v_pk_mul_f32 v[18:19], v[18:19], v[20:21]
	v_cvt_pk_bf16_f32 v218, v16, v17
	v_cvt_pk_bf16_f32 v219, v18, v19
	v_mov_b64_e32 v[18:19], s[12:13]
	v_mad_u64_u32 v[18:19], s[26:27], v96, s66, v[18:19]
	v_lshl_add_u64 v[18:19], v[88:89], 1, v[18:19]
	v_add_co_u32_e32 v18, vcc, 0xfffea000, v18
	s_nop 1
	v_addc_co_u32_e32 v19, vcc, -1, v19, vcc
	global_store_dwordx4 v[18:19], v[216:219], off offset:-8
; #define LAS __attribute__((address_space(3)))
; __device__ __forceinline__ unsigned pk2e(float lo, float hi) { typedef __bf16 b2 __attribute__((ext_vector_type(2))); b2 v; v.x = (__bf16)lo; v.y = (__bf16)hi; return __builtin_bit_cast(unsigned, v); }
; __device__ __forceinline__ float ex2(float x) { return __builtin_amdgcn_exp2f(x); }
;     __device__ __forceinline__ void operator()(const f32x4 (&acc)[2][2][4][2], const Unit& u, int wr, int wc, int fr, int fq, LAS unsigned char* hb) const {
;     ...
;                 for (int m = 0; m < 4; ++m) { const int q = 8 * ai + 4 * wr + m, prev = q > 0 ? q - 1 : 0; const int lr = ai * HALF + wr * 64 + m * 16 + fr, R = R0 + lr;
;                     const int Rc = R < 0 ? 0 : R; const int b = Rc / LL, p = Rc - b * LL;
;                     const LAS unsigned char* hp = hb + (prev * H * NCH + chl + 4 * n) * 4;
;                     const f32x4 h1 = *(const LAS f32x4*)(hp + hr1 * NCH * 4), h2 = *(const LAS f32x4*)(hp + hr2 * NCH * 4);
;                     const f32x4 gv = acc[ai][0][m][n], uv = acc[ai][1][m][n];
;                     float o[4];
; #pragma unroll
;                     for (int j = 0; j < 4; ++j) { const float g = gv[j];
;                         float g1 = dpp_row_shr<1>(h1[j], g), g2 = dpp_row_shr<2>(h2[j], g);
;                         g1 = p >= 1 ? g1 : 0.f; g2 = p >= 2 ? g2 : 0.f;
;                         const float v = bs[j] + w2[j] * g + w1[j] * g1 + w0[j] * g2;
;                         const float a = v + 0.044715f * v * v * v;
;                         const float ge = v * __builtin_amdgcn_rcpf(1.f + ex2(-2.f * 0.7978845608028654f * 1.4426950408889634f * a));
;                         o[j] = ge * uv[j]; }
;                     if (lr >= H && R < TT && p >= NMETA) { u32x2 w; w.x = pk2e(o[0], o[1]); w.y = pk2e(o[2], o[3]);
;                         *(u32x2*)(ACT + ((size_t)b * SEQ + p - NMETA) * DFF + c4) = w; } }
.LBB0_916:
	s_or_b64 exec, exec, s[8:9]
	ds_read_b128 v[20:23], v92 offset:9744
	ds_read_b128 v[16:19], v93 offset:9232
	s_waitcnt lgkmcnt(0)
	v_mov_b32_dpp v20, v12 row_shr:1 row_mask:0xf bank_mask:0xf
	v_mov_b32_dpp v16, v12 row_shr:2 row_mask:0xf bank_mask:0xf
	v_mov_b32_dpp v21, v13 row_shr:1 row_mask:0xf bank_mask:0xf
	v_mov_b32_dpp v17, v13 row_shr:2 row_mask:0xf bank_mask:0xf
	v_mov_b32_dpp v22, v14 row_shr:1 row_mask:0xf bank_mask:0xf
	v_mov_b32_dpp v18, v14 row_shr:2 row_mask:0xf bank_mask:0xf
	v_mov_b32_dpp v23, v15 row_shr:1 row_mask:0xf bank_mask:0xf
	v_mov_b32_dpp v19, v15 row_shr:2 row_mask:0xf bank_mask:0xf
	s_and_saveexec_b64 s[8:9], s[40:41]
	s_cbranch_execz .LBB0_918
	v_pk_fma_f32 v[12:13], v[12:13], v[72:73], v[76:77]
	v_pk_fma_f32 v[14:15], v[14:15], v[74:75], v[78:79]
	v_pk_fma_f32 v[12:13], v[68:69], v[20:21], v[12:13]
	v_pk_fma_f32 v[14:15], v[70:71], v[22:23], v[14:15]
	v_pk_fma_f32 v[12:13], v[60:61], v[16:17], v[12:13]
	v_pk_fma_f32 v[14:15], v[62:63], v[18:19], v[14:15]
	v_mul_f32_e32 v16, 0x3d372713, v13
	v_mul_f32_e32 v16, v13, v16
	v_mul_f32_e32 v17, 0x3d372713, v12
	v_fma_f32 v16, v13, v16, v13
	v_mul_f32_e32 v17, v12, v17
	v_mul_f32_e32 v16, 0xc0135761, v16
	v_fma_f32 v17, v12, v17, v12
	v_exp_f32_e32 v16, v16
	v_mul_f32_e32 v17, 0xc0135761, v17
	v_mul_f32_e32 v18, 0x3d372713, v15
	v_exp_f32_e32 v20, v17
	v_mul_f32_e32 v18, v15, v18
	v_mul_f32_e32 v19, 0x3d372713, v14
	v_fma_f32 v18, v15, v18, v15
	v_mul_f32_e32 v19, v14, v19
	v_mul_f32_e32 v18, 0xc0135761, v18
	v_fma_f32 v19, v14, v19, v14
	v_add_f32_e32 v16, 1.0, v16
	v_exp_f32_e32 v18, v18
	v_mul_f32_e32 v19, 0xc0135761, v19
	v_rcp_f32_e32 v17, v16
	v_add_f32_e32 v16, 1.0, v20
	v_exp_f32_e32 v20, v19
	v_add_f32_e32 v18, 1.0, v18
	v_rcp_f32_e32 v16, v16
	v_rcp_f32_e32 v19, v18
	v_add_f32_e32 v18, 1.0, v20
	v_rcp_f32_e32 v18, v18
	v_pk_mul_f32 v[12:13], v[12:13], v[16:17]
	v_readlane_b32 s12, v237, 50
	v_pk_mul_f32 v[8:9], v[8:9], v[12:13]
	v_pk_mul_f32 v[12:13], v[14:15], v[18:19]
	v_readlane_b32 s13, v237, 51
	v_pk_mul_f32 v[10:11], v[10:11], v[12:13]
	v_cvt_pk_bf16_f32 v230, v8, v9
	v_cvt_pk_bf16_f32 v231, v10, v11
	v_mov_b64_e32 v[10:11], s[12:13]
	v_mad_u64_u32 v[10:11], s[26:27], v90, s66, v[10:11]
	v_lshl_add_u64 v[10:11], v[88:89], 1, v[10:11]
	v_add_co_u32_e32 v10, vcc, 0xfffea000, v10
	s_nop 1
	v_addc_co_u32_e32 v11, vcc, -1, v11, vcc
	global_store_dwordx4 v[10:11], v[228:231], off offset:-8
.LBB0_918:
	s_or_b64 exec, exec, s[8:9]
	ds_read_b128 v[12:15], v94 offset:10768
	ds_read_b128 v[8:11], v95 offset:10256
	s_waitcnt lgkmcnt(0)
	v_mov_b32_dpp v12, v4 row_shr:1 row_mask:0xf bank_mask:0xf
	v_mov_b32_dpp v8, v4 row_shr:2 row_mask:0xf bank_mask:0xf
	v_mov_b32_dpp v13, v5 row_shr:1 row_mask:0xf bank_mask:0xf
	v_mov_b32_dpp v9, v5 row_shr:2 row_mask:0xf bank_mask:0xf
	v_mov_b32_dpp v14, v6 row_shr:1 row_mask:0xf bank_mask:0xf
	v_mov_b32_dpp v10, v6 row_shr:2 row_mask:0xf bank_mask:0xf
	v_mov_b32_dpp v15, v7 row_shr:1 row_mask:0xf bank_mask:0xf
	v_mov_b32_dpp v11, v7 row_shr:2 row_mask:0xf bank_mask:0xf
	s_and_saveexec_b64 s[8:9], s[6:7]
	s_cbranch_execz .LBB0_920
	v_pk_fma_f32 v[4:5], v[4:5], v[72:73], v[76:77]
	v_pk_fma_f32 v[6:7], v[6:7], v[74:75], v[78:79]
	v_pk_fma_f32 v[4:5], v[68:69], v[12:13], v[4:5]
	v_pk_fma_f32 v[6:7], v[70:71], v[14:15], v[6:7]
	v_pk_fma_f32 v[4:5], v[60:61], v[8:9], v[4:5]
	v_pk_fma_f32 v[6:7], v[62:63], v[10:11], v[6:7]
	v_mul_f32_e32 v8, 0x3d372713, v5
	v_mul_f32_e32 v8, v5, v8
	v_mul_f32_e32 v9, 0x3d372713, v4
	v_fma_f32 v8, v5, v8, v5
	v_mul_f32_e32 v9, v4, v9
	v_mul_f32_e32 v8, 0xc0135761, v8
	v_fma_f32 v9, v4, v9, v4
	v_exp_f32_e32 v8, v8
	v_mul_f32_e32 v9, 0xc0135761, v9
	v_mul_f32_e32 v10, 0x3d372713, v7
	v_exp_f32_e32 v12, v9
	v_mul_f32_e32 v10, v7, v10
	v_mul_f32_e32 v11, 0x3d372713, v6
	v_fma_f32 v10, v7, v10, v7
	v_mul_f32_e32 v11, v6, v11
	v_mul_f32_e32 v10, 0xc0135761, v10
	v_fma_f32 v11, v6, v11, v6
	v_add_f32_e32 v8, 1.0, v8
	v_exp_f32_e32 v10, v10
	v_mul_f32_e32 v11, 0xc0135761, v11
	v_rcp_f32_e32 v9, v8
	v_add_f32_e32 v8, 1.0, v12
	v_exp_f32_e32 v12, v11
	v_add_f32_e32 v10, 1.0, v10
	v_rcp_f32_e32 v8, v8
	v_rcp_f32_e32 v11, v10
	v_add_f32_e32 v10, 1.0, v12
	v_rcp_f32_e32 v10, v10
	v_pk_mul_f32 v[4:5], v[4:5], v[8:9]
	v_readlane_b32 s6, v237, 50
	v_pk_mul_f32 v[0:1], v[0:1], v[4:5]
	v_pk_mul_f32 v[4:5], v[6:7], v[10:11]
	v_readlane_b32 s7, v237, 51
	v_pk_mul_f32 v[2:3], v[2:3], v[4:5]
	v_cvt_pk_bf16_f32 v234, v0, v1
	v_cvt_pk_bf16_f32 v235, v2, v3
	v_mov_b64_e32 v[2:3], s[6:7]
	v_mad_u64_u32 v[2:3], s[6:7], v91, s66, v[2:3]
	v_lshl_add_u64 v[2:3], v[88:89], 1, v[2:3]
	v_add_co_u32_e32 v2, vcc, 0xfffea000, v2
	s_nop 1
	v_addc_co_u32_e32 v3, vcc, -1, v3, vcc
	global_store_dwordx4 v[2:3], v[232:235], off offset:-8
